# phase-0 rownorm_first software-pipelined (gains hoisted, 2 rows/iter, next pair prefetched, counted vmcnt) on top of trim+defer
# speedup vs baseline: 1.0031x; 1.0007x over previous
; #define tid fresh_tid(wave_s)
; __device__ __forceinline__ void rownorm_first(const float* x, const float* g, bf16_t* a, int nrows, int tid, int bx) {
;     const int lane = tid & 63, wave = tid >> 6;
;     for (int row = bx * 8 + wave; row < nrows; row += gridDim.x * 8) {
;         float4 v[4]; float ss = 0.f;
; #pragma unroll
;         for (int i = 0; i < 4; ++i) { v[i] = *(const float4*)(x + (size_t)row * 1024 + i * 256 + lane * 4); ss += v[i].x * v[i].x + v[i].y * v[i].y + v[i].z * v[i].z + v[i].w * v[i].w; }
.LBB0_11:
	s_cmpk_lg_u32 s3, 0x100
	s_cbranch_scc1 .Lrn_orig
	v_readfirstlane_b32 s80, v2
	global_load_dwordx4 v[84:87], v[6:7], off
	global_load_dwordx4 v[88:91], v[6:7], off offset:1024
	global_load_dwordx4 v[92:95], v[6:7], off offset:2048
	global_load_dwordx4 v[96:99], v[6:7], off offset:3072
	s_lshl_b32 s82, s80, 12
	s_mov_b32 s83, 0
	v_lshl_add_u64 v[120:121], v[4:5], 0, s[82:83]
	s_add_u32 s82, s82, 0x800000
	v_lshl_add_u64 v[122:123], v[4:5], 0, s[82:83]
	global_load_dwordx4 v[20:23], v[120:121], off
	global_load_dwordx4 v[24:27], v[120:121], off offset:1024
	global_load_dwordx4 v[28:31], v[120:121], off offset:2048
	global_load_dwordx4 v[32:35], v[120:121], off offset:3072
	global_load_dwordx4 v[36:39], v[122:123], off
	global_load_dwordx4 v[40:43], v[122:123], off offset:1024
	global_load_dwordx4 v[44:47], v[122:123], off offset:2048
	global_load_dwordx4 v[48:51], v[122:123], off offset:3072
	s_waitcnt vmcnt(0)
	s_branch .Lrn_body
.Lrn_top:
	s_waitcnt vmcnt(8)
.Lrn_body:
	v_mov_b32_e32 v52, v20
	v_mov_b32_e32 v53, v21
	v_mov_b32_e32 v54, v22
	v_mov_b32_e32 v55, v23
	v_mov_b32_e32 v56, v24
	v_mov_b32_e32 v57, v25
	v_mov_b32_e32 v58, v26
	v_mov_b32_e32 v59, v27
	v_mov_b32_e32 v60, v28
	v_mov_b32_e32 v61, v29
	v_mov_b32_e32 v62, v30
	v_mov_b32_e32 v63, v31
	v_mov_b32_e32 v64, v32
	v_mov_b32_e32 v65, v33
	v_mov_b32_e32 v66, v34
	v_mov_b32_e32 v67, v35
	v_mov_b32_e32 v68, v36
	v_mov_b32_e32 v69, v37
	v_mov_b32_e32 v70, v38
	v_mov_b32_e32 v71, v39
	v_mov_b32_e32 v72, v40
	v_mov_b32_e32 v73, v41
	v_mov_b32_e32 v74, v42
	v_mov_b32_e32 v75, v43
	v_mov_b32_e32 v76, v44
	v_mov_b32_e32 v77, v45
	v_mov_b32_e32 v78, v46
	v_mov_b32_e32 v79, v47
	v_mov_b32_e32 v80, v48
	v_mov_b32_e32 v81, v49
	v_mov_b32_e32 v82, v50
	v_mov_b32_e32 v83, v51
	s_lshl_b32 s82, s80, 11
	s_mov_b32 s83, 0
	v_lshl_add_u64 v[124:125], v[8:9], 0, s[82:83]
	s_add_u32 s82, s82, 0x400000
	v_lshl_add_u64 v[126:127], v[8:9], 0, s[82:83]
	s_add_i32 s81, s80, 0x1000
	s_cmp_lt_i32 s81, 0x8000
	s_cbranch_scc0 .Lrn_nopf
	s_lshl_b32 s82, s81, 12
	s_mov_b32 s83, 0
	v_lshl_add_u64 v[120:121], v[4:5], 0, s[82:83]
	s_add_u32 s82, s82, 0x800000
	v_lshl_add_u64 v[122:123], v[4:5], 0, s[82:83]
	global_load_dwordx4 v[20:23], v[120:121], off
	global_load_dwordx4 v[24:27], v[120:121], off offset:1024
	global_load_dwordx4 v[28:31], v[120:121], off offset:2048
	global_load_dwordx4 v[32:35], v[120:121], off offset:3072
	global_load_dwordx4 v[36:39], v[122:123], off
	global_load_dwordx4 v[40:43], v[122:123], off offset:1024
	global_load_dwordx4 v[44:47], v[122:123], off offset:2048
	global_load_dwordx4 v[48:51], v[122:123], off offset:3072
; __device__ __forceinline__ void rownorm_first(const float* x, const float* g, bf16_t* a, int nrows, int tid, int bx) {
;     ...
;         for (int i = 0; i < 4; ++i) { v[i] = *(const float4*)(x + (size_t)row * 1024 + i * 256 + lane * 4); ss += v[i].x * v[i].x + v[i].y * v[i].y + v[i].z * v[i].z + v[i].w * v[i].w; }
;         ss = wave_sum(ss); const float rs = 1.0f / sqrtf(ss * (1.0f / 1024.0f) + 1e-6f);
; #pragma unroll
;         for (int i = 0; i < 4; ++i) { const float4 gg = *(const float4*)(g + i * 256 + lane * 4);
;             u32x2 w; w.x = cvt_pk_bf16(v[i].x * rs * gg.x, v[i].y * rs * gg.y); w.y = cvt_pk_bf16(v[i].z * rs * gg.z, v[i].w * rs * gg.w);
;             *(u32x2*)(a + (size_t)row * 1024 + i * 256 + lane * 4) = w; }
;     }
.Lrn_nopf:
	v_pk_mul_f32 v[100:101], v[52:53], v[52:53]
	v_pk_fma_f32 v[100:101], v[54:55], v[54:55], v[100:101]
	v_pk_fma_f32 v[100:101], v[56:57], v[56:57], v[100:101]
	v_pk_fma_f32 v[100:101], v[58:59], v[58:59], v[100:101]
	v_pk_fma_f32 v[100:101], v[60:61], v[60:61], v[100:101]
	v_pk_fma_f32 v[100:101], v[62:63], v[62:63], v[100:101]
	v_pk_fma_f32 v[100:101], v[64:65], v[64:65], v[100:101]
	v_pk_fma_f32 v[100:101], v[66:67], v[66:67], v[100:101]
	v_add_f32_e32 v100, v100, v101
	v_pk_mul_f32 v[102:103], v[68:69], v[68:69]
	v_pk_fma_f32 v[102:103], v[70:71], v[70:71], v[102:103]
	v_pk_fma_f32 v[102:103], v[72:73], v[72:73], v[102:103]
	v_pk_fma_f32 v[102:103], v[74:75], v[74:75], v[102:103]
	v_pk_fma_f32 v[102:103], v[76:77], v[76:77], v[102:103]
	v_pk_fma_f32 v[102:103], v[78:79], v[78:79], v[102:103]
	v_pk_fma_f32 v[102:103], v[80:81], v[80:81], v[102:103]
	v_pk_fma_f32 v[102:103], v[82:83], v[82:83], v[102:103]
	v_add_f32_e32 v102, v102, v103
	ds_bpermute_b32 v104, v12, v100
	ds_bpermute_b32 v105, v12, v102
	s_waitcnt lgkmcnt(1)
	v_add_f32_e32 v100, v100, v104
	s_waitcnt lgkmcnt(0)
	v_add_f32_e32 v102, v102, v105
	ds_bpermute_b32 v104, v13, v100
	ds_bpermute_b32 v105, v13, v102
	s_waitcnt lgkmcnt(1)
	v_add_f32_e32 v100, v100, v104
	s_waitcnt lgkmcnt(0)
	v_add_f32_e32 v102, v102, v105
	ds_bpermute_b32 v104, v14, v100
	ds_bpermute_b32 v105, v14, v102
	s_waitcnt lgkmcnt(1)
	v_add_f32_e32 v100, v100, v104
	s_waitcnt lgkmcnt(0)
	v_add_f32_e32 v102, v102, v105
	ds_bpermute_b32 v104, v15, v100
	ds_bpermute_b32 v105, v15, v102
	s_waitcnt lgkmcnt(1)
	v_add_f32_e32 v100, v100, v104
	s_waitcnt lgkmcnt(0)
	v_add_f32_e32 v102, v102, v105
	ds_bpermute_b32 v104, v16, v100
	ds_bpermute_b32 v105, v16, v102
	s_waitcnt lgkmcnt(1)
	v_add_f32_e32 v100, v100, v104
	s_waitcnt lgkmcnt(0)
	v_add_f32_e32 v102, v102, v105
	ds_bpermute_b32 v104, v17, v100
	ds_bpermute_b32 v105, v17, v102
	s_waitcnt lgkmcnt(1)
	v_add_f32_e32 v100, v100, v104
	s_waitcnt lgkmcnt(0)
	v_add_f32_e32 v102, v102, v105
	v_fmamk_f32 v100, v100, 0x3a800000, v18
	v_fmamk_f32 v102, v102, 0x3a800000, v18
	v_cmp_gt_f32_e32 vcc, s18, v100
	v_mul_f32_e32 v104, 0x4f800000, v100
	s_nop 0
	v_cndmask_b32_e32 v100, v100, v104, vcc
	v_sqrt_f32_e32 v104, v100
	s_nop 0
	v_add_u32_e32 v105, -1, v104
	v_fma_f32 v106, -v105, v104, v100
	v_cmp_ge_f32_e64 s[84:85], 0, v106
	v_add_u32_e32 v107, 1, v104
	s_nop 0
	v_cndmask_b32_e64 v105, v104, v105, s[84:85]
	v_fma_f32 v104, -v107, v104, v100
	v_cmp_lt_f32_e64 s[84:85], 0, v104
	s_nop 1
	v_cndmask_b32_e64 v104, v105, v107, s[84:85]
	v_mul_f32_e32 v105, 0x37800000, v104
	v_cndmask_b32_e32 v104, v104, v105, vcc
	v_cmp_class_f32_e32 vcc, v100, v19
	s_nop 1
	v_cndmask_b32_e32 v108, v104, v100, vcc
	v_div_scale_f32 v104, s[86:87], v108, v108, 1.0
	v_rcp_f32_e32 v105, v104
	s_nop 0
	v_fma_f32 v106, -v104, v105, 1.0
	v_fmac_f32_e32 v105, v106, v105
	v_div_scale_f32 v106, vcc, 1.0, v108, 1.0
	v_mul_f32_e32 v107, v106, v105
	v_fma_f32 v100, -v104, v107, v106
	v_fmac_f32_e32 v107, v100, v105
	v_fma_f32 v104, -v104, v107, v106
	v_div_fmas_f32 v104, v104, v105, v107
	v_div_fixup_f32 v116, v104, v108, 1.0
	v_cmp_gt_f32_e32 vcc, s18, v102
	v_mul_f32_e32 v104, 0x4f800000, v102
	s_nop 0
	v_cndmask_b32_e32 v102, v102, v104, vcc
	v_sqrt_f32_e32 v104, v102
	s_nop 0
	v_add_u32_e32 v105, -1, v104
	v_fma_f32 v106, -v105, v104, v102
	v_cmp_ge_f32_e64 s[84:85], 0, v106
	v_add_u32_e32 v107, 1, v104
	s_nop 0
	v_cndmask_b32_e64 v105, v104, v105, s[84:85]
	v_fma_f32 v104, -v107, v104, v102
	v_cmp_lt_f32_e64 s[84:85], 0, v104
	s_nop 1
	v_cndmask_b32_e64 v104, v105, v107, s[84:85]
	v_mul_f32_e32 v105, 0x37800000, v104
	v_cndmask_b32_e32 v104, v104, v105, vcc
	v_cmp_class_f32_e32 vcc, v102, v19
	s_nop 1
	v_cndmask_b32_e32 v108, v104, v102, vcc
	v_div_scale_f32 v104, s[86:87], v108, v108, 1.0
	v_rcp_f32_e32 v105, v104
	s_nop 0
	v_fma_f32 v106, -v104, v105, 1.0
	v_fmac_f32_e32 v105, v106, v105
	v_div_scale_f32 v106, vcc, 1.0, v108, 1.0
	v_mul_f32_e32 v107, v106, v105
	v_fma_f32 v102, -v104, v107, v106
	v_fmac_f32_e32 v107, v102, v105
	v_fma_f32 v104, -v104, v107, v106
	v_div_fmas_f32 v104, v104, v105, v107
	v_div_fixup_f32 v118, v104, v108, 1.0
	v_pk_mul_f32 v[52:53], v[52:53], v[116:117] op_sel_hi:[1,0]
	v_pk_mul_f32 v[52:53], v[84:85], v[52:53]
	v_pk_mul_f32 v[54:55], v[54:55], v[116:117] op_sel_hi:[1,0]
	v_pk_mul_f32 v[54:55], v[86:87], v[54:55]
	v_cvt_pk_bf16_f32 v52, v52, v53
	v_cvt_pk_bf16_f32 v53, v54, v55
	global_store_dwordx2 v[124:125], v[52:53], off
	v_pk_mul_f32 v[56:57], v[56:57], v[116:117] op_sel_hi:[1,0]
	v_pk_mul_f32 v[56:57], v[88:89], v[56:57]
	v_pk_mul_f32 v[58:59], v[58:59], v[116:117] op_sel_hi:[1,0]
	v_pk_mul_f32 v[58:59], v[90:91], v[58:59]
	v_cvt_pk_bf16_f32 v56, v56, v57
	v_cvt_pk_bf16_f32 v57, v58, v59
	global_store_dwordx2 v[124:125], v[56:57], off offset:512
	v_pk_mul_f32 v[60:61], v[60:61], v[116:117] op_sel_hi:[1,0]
	v_pk_mul_f32 v[60:61], v[92:93], v[60:61]
	v_pk_mul_f32 v[62:63], v[62:63], v[116:117] op_sel_hi:[1,0]
	v_pk_mul_f32 v[62:63], v[94:95], v[62:63]
	v_cvt_pk_bf16_f32 v60, v60, v61
	v_cvt_pk_bf16_f32 v61, v62, v63
	global_store_dwordx2 v[124:125], v[60:61], off offset:1024
	v_pk_mul_f32 v[64:65], v[64:65], v[116:117] op_sel_hi:[1,0]
	v_pk_mul_f32 v[64:65], v[96:97], v[64:65]
	v_pk_mul_f32 v[66:67], v[66:67], v[116:117] op_sel_hi:[1,0]
	v_pk_mul_f32 v[66:67], v[98:99], v[66:67]
	v_cvt_pk_bf16_f32 v64, v64, v65
	v_cvt_pk_bf16_f32 v65, v66, v67
	global_store_dwordx2 v[124:125], v[64:65], off offset:1536
	v_pk_mul_f32 v[68:69], v[68:69], v[118:119] op_sel_hi:[1,0]
	v_pk_mul_f32 v[68:69], v[84:85], v[68:69]
	v_pk_mul_f32 v[70:71], v[70:71], v[118:119] op_sel_hi:[1,0]
	v_pk_mul_f32 v[70:71], v[86:87], v[70:71]
	v_cvt_pk_bf16_f32 v68, v68, v69
	v_cvt_pk_bf16_f32 v69, v70, v71
	global_store_dwordx2 v[126:127], v[68:69], off
	v_pk_mul_f32 v[72:73], v[72:73], v[118:119] op_sel_hi:[1,0]
	v_pk_mul_f32 v[72:73], v[88:89], v[72:73]
	v_pk_mul_f32 v[74:75], v[74:75], v[118:119] op_sel_hi:[1,0]
	v_pk_mul_f32 v[74:75], v[90:91], v[74:75]
	v_cvt_pk_bf16_f32 v72, v72, v73
	v_cvt_pk_bf16_f32 v73, v74, v75
	global_store_dwordx2 v[126:127], v[72:73], off offset:512
	v_pk_mul_f32 v[76:77], v[76:77], v[118:119] op_sel_hi:[1,0]
	v_pk_mul_f32 v[76:77], v[92:93], v[76:77]
	v_pk_mul_f32 v[78:79], v[78:79], v[118:119] op_sel_hi:[1,0]
	v_pk_mul_f32 v[78:79], v[94:95], v[78:79]
	v_cvt_pk_bf16_f32 v76, v76, v77
	v_cvt_pk_bf16_f32 v77, v78, v79
	global_store_dwordx2 v[126:127], v[76:77], off offset:1024
	v_pk_mul_f32 v[80:81], v[80:81], v[118:119] op_sel_hi:[1,0]
	v_pk_mul_f32 v[80:81], v[96:97], v[80:81]
	v_pk_mul_f32 v[82:83], v[82:83], v[118:119] op_sel_hi:[1,0]
	v_pk_mul_f32 v[82:83], v[98:99], v[82:83]
	v_cvt_pk_bf16_f32 v80, v80, v81
	v_cvt_pk_bf16_f32 v81, v82, v83
	global_store_dwordx2 v[126:127], v[80:81], off offset:1536
	s_mov_b32 s80, s81
	s_cmp_lt_i32 s80, 0x8000
	s_cbranch_scc1 .Lrn_top
	s_branch .LBB0_12
